# mixer-in and residual GEMM loops: in the peeled first K-iteration the first two vmcnt(8) waits apply to the first tile of a phase only
# baseline (speedup 1.0000x reference)
; #define PG8_STAGE(bufoff, gbase, voff) do { _Pragma("unroll") for (int _i = 0; _i < 2; ++_i) \
;         __builtin_amdgcn_global_load_lds((const unsigned*)((const char*)(gbase) + (voff)[_i]), (PG8_LAS unsigned*)(lds + (bufoff) + ldsw + _i * 8192), 16, 0, 0); } while (0)
; #define PG8_LDA(dst, b, h) do { _Pragma("unroll") for (int m = 0; m < 4; ++m) _Pragma("unroll") for (int k = 0; k < 2; ++k) dst[m][k] = *(const PG8_LAS bf16x8*)(lds + PG8_SA(b, h) + aoff + m * 2048 + k * 1024); } while (0)
; #define PG8_LDB(dst, b, h) do { _Pragma("unroll") for (int n = 0; n < 2; ++n) _Pragma("unroll") for (int k = 0; k < 2; ++k) dst[n][k] = *(const PG8_LAS bf16x8*)(lds + PG8_SB(b, h) + boff + n * 2048 + k * 1024); } while (0)
; #define PG8_MMA(ai, bj, At, Bt) do { __builtin_amdgcn_s_setprio(1); _Pragma("unroll") for (int m = 0; m < 4; ++m) _Pragma("unroll") for (int n = 0; n < 2; ++n) _Pragma("unroll") for (int k = 0; k < 2; ++k) \
;         acc[ai][bj][m][n] = __builtin_amdgcn_mfma_f32_16x16x32_bf16(Bt[n][k], At[m][k], acc[ai][bj][m][n], 0, 0, 0); __builtin_amdgcn_s_setprio(0); } while (0)
; #define PG8_WAIT_V(n) asm volatile("s_waitcnt vmcnt(" #n ")" ::: "memory")
; #define PG8_WAIT_L(n) asm volatile("s_waitcnt lgkmcnt(" #n ")" ::: "memory")
; #define PG8_BAR __builtin_amdgcn_s_barrier()
; #define PG8_SCHED __builtin_amdgcn_sched_barrier(0)
; template <class Epi, class Sched, bool ALIGN_EPI = false, bool SP2 = false>
; __device__ __forceinline__ void gemm_phase(PG8_LAS unsigned char* lds, const Gemm g, const Sched& S, const Epi& E, const int tid_) {
;     ...
;             const bool last = (t == nt - 2);
;             const char* a1 = cA + (size_t)(t + 1) * kstep;
;             const char* a2 = last ? nA : cA + (size_t)(t + 2) * kstep; const char* b2 = last ? nB : cB + (size_t)(t + 2) * kstep;
;             const char* a3 = a2 + kstep; const char* b3 = b2 + kstep;
;             if (last && has_next) S.a_ready(nxt);
;             if constexpr (SP2) {
;             PG8_LDB(B0, 0, 0); PG8_LDB(B1, 0, 1); PG8_SCHED; PG8_LDA(At, 0, 0); PG8_STAGE(PG8_SA(1, 1), a1 + hstep, voffA);
;             PG8_WAIT_V(8); PG8_WAIT_L(0); PG8_BAR; PG8_MMA(0, 0, At, B0); PG8_MMA(0, 1, At, B1); PG8_BAR; PG8_SCHED;
;             PG8_LDA(At, 0, 1); PG8_STAGE(PG8_SB(0, 0), b2, voffB); PG8_STAGE(PG8_SB(0, 1), b2 + hstepB, voffB); PG8_STAGE(PG8_SA(0, 0), a2, voffA);
.LBB0_368:
	s_add_u32 s8, s52, 0x80
	s_addc_u32 s9, s53, 0
	s_add_u32 s2, s12, 0x100
	s_addc_u32 s3, s13, 0
	s_mov_b32 s10, 0
	s_waitcnt lgkmcnt(0)
	v_add_u32_e32 v40, s61, v197
	v_add_u32_e32 v160, s64, v197
	ds_read_b128 v[12:15], v40
	ds_read_b128 v[16:19], v40 offset:1024
	ds_read_b128 v[36:39], v40 offset:2048
	ds_read_b128 v[40:43], v40 offset:3072
	ds_read_b128 v[148:151], v160
	ds_read_b128 v[152:155], v160 offset:1024
	ds_read_b128 v[156:159], v160 offset:2048
	ds_read_b128 v[160:163], v160 offset:3072
	s_add_i32 s12, s10, 2
	s_add_u32 s13, s8, 0x80
	s_addc_u32 s11, s9, 0
	s_cmp_eq_u32 s82, s10
	s_cselect_b32 s10, s48, s13
	s_cselect_b32 s11, s49, s11
	s_cselect_b32 s53, s51, s3
	s_cselect_b32 s52, s50, s2
	v_lshl_add_u64 v[194:195], s[8:9], 0, v[190:191]
	s_add_i32 m0, s67, 0xc000
	ds_read_b128 v[164:167], v238
	ds_read_b128 v[168:171], v238 offset:1024
	ds_read_b128 v[198:201], v238 offset:2048
	ds_read_b128 v[202:205], v238 offset:3072
	ds_read_b128 v[206:209], v238 offset:4096
	ds_read_b128 v[210:213], v238 offset:5120
	ds_read_b128 v[214:217], v238 offset:6144
	ds_read_b128 v[218:221], v238 offset:7168
	global_load_lds_dwordx4 v[194:195], off
	v_lshl_add_u64 v[194:195], s[8:9], 0, v[192:193]
	s_add_i32 m0, s67, 0xe000
	s_nop 0
	global_load_lds_dwordx4 v[194:195], off
	s_cmp_lg_u32 s86, 1
	s_cbranch_scc1 .Lpeel2_mx0
	s_waitcnt vmcnt(8)
.Lpeel2_mx0:
	s_waitcnt lgkmcnt(0)
	s_barrier
	s_setprio 1
	s_waitcnt lgkmcnt(0)
	v_mfma_f32_16x16x32_bf16 v[144:147], v[12:15], v[164:167], 0
	v_mfma_f32_16x16x32_bf16 v[140:143], v[36:39], v[164:167], 0
	v_mfma_f32_16x16x32_bf16 v[128:131], v[12:15], v[198:201], 0
	v_mfma_f32_16x16x32_bf16 v[124:127], v[36:39], v[198:201], 0
	v_mfma_f32_16x16x32_bf16 v[112:115], v[12:15], v[206:209], 0
	v_mfma_f32_16x16x32_bf16 v[108:111], v[36:39], v[206:209], 0
	v_mfma_f32_16x16x32_bf16 v[96:99], v[12:15], v[214:217], 0
	v_mfma_f32_16x16x32_bf16 v[92:95], v[36:39], v[214:217], 0
	v_mfma_f32_16x16x32_bf16 v[144:147], v[16:19], v[168:171], v[144:147]
	v_mfma_f32_16x16x32_bf16 v[140:143], v[40:43], v[168:171], v[140:143]
	v_mfma_f32_16x16x32_bf16 v[128:131], v[16:19], v[202:205], v[128:131]
	v_mfma_f32_16x16x32_bf16 v[124:127], v[40:43], v[202:205], v[124:127]
	v_mfma_f32_16x16x32_bf16 v[112:115], v[16:19], v[210:213], v[112:115]
	v_mfma_f32_16x16x32_bf16 v[108:111], v[40:43], v[210:213], v[108:111]
	v_mfma_f32_16x16x32_bf16 v[96:99], v[16:19], v[218:221], v[96:99]
	v_mfma_f32_16x16x32_bf16 v[92:95], v[40:43], v[218:221], v[92:95]
	s_setprio 0
	s_setprio 1
	v_mfma_f32_16x16x32_bf16 v[136:139], v[148:151], v[164:167], 0
	v_mfma_f32_16x16x32_bf16 v[132:135], v[156:159], v[164:167], 0
	v_mfma_f32_16x16x32_bf16 v[120:123], v[148:151], v[198:201], 0
	v_mfma_f32_16x16x32_bf16 v[116:119], v[156:159], v[198:201], 0
	v_mfma_f32_16x16x32_bf16 v[104:107], v[148:151], v[206:209], 0
	v_mfma_f32_16x16x32_bf16 v[100:103], v[156:159], v[206:209], 0
	v_mfma_f32_16x16x32_bf16 v[88:91], v[148:151], v[214:217], 0
	v_mfma_f32_16x16x32_bf16 v[84:87], v[156:159], v[214:217], 0
	v_mfma_f32_16x16x32_bf16 v[136:139], v[152:155], v[168:171], v[136:139]
	v_mfma_f32_16x16x32_bf16 v[132:135], v[160:163], v[168:171], v[132:135]
	v_mfma_f32_16x16x32_bf16 v[120:123], v[152:155], v[202:205], v[120:123]
	v_mfma_f32_16x16x32_bf16 v[116:119], v[160:163], v[202:205], v[116:119]
	v_mfma_f32_16x16x32_bf16 v[104:107], v[152:155], v[210:213], v[104:107]
	v_mfma_f32_16x16x32_bf16 v[100:103], v[160:163], v[210:213], v[100:103]
	v_mfma_f32_16x16x32_bf16 v[88:91], v[152:155], v[218:221], v[88:91]
	v_mfma_f32_16x16x32_bf16 v[84:87], v[160:163], v[218:221], v[84:87]
	s_setprio 0
	s_barrier
	s_mov_b32 m0, s62
	v_lshl_add_u64 v[194:195], s[52:53], 0, v[172:173]
	v_lshl_add_u64 v[222:223], s[52:53], 0, v[176:177]
	s_add_u32 s52, s52, s38
	ds_read_b128 v[164:167], v238 offset:16384
	ds_read_b128 v[168:171], v238 offset:17408
	ds_read_b128 v[198:201], v238 offset:18432
	ds_read_b128 v[202:205], v238 offset:19456
	ds_read_b128 v[206:209], v238 offset:20480
	ds_read_b128 v[210:213], v238 offset:21504
	ds_read_b128 v[214:217], v238 offset:22528
	ds_read_b128 v[218:221], v238 offset:23552
	global_load_lds_dwordx4 v[194:195], off
	s_mov_b32 m0, s63
	s_addc_u32 s53, s53, s39
	global_load_lds_dwordx4 v[222:223], off
	v_lshl_add_u64 v[224:225], s[52:53], 0, v[172:173]
	s_mov_b32 m0, s65
	v_lshl_add_u64 v[226:227], s[52:53], 0, v[176:177]
	global_load_lds_dwordx4 v[224:225], off
	s_mov_b32 m0, s66
	v_lshl_add_u64 v[228:229], s[10:11], 0, v[0:1]
	global_load_lds_dwordx4 v[226:227], off
	s_mov_b32 m0, s67
	v_lshl_add_u64 v[230:231], s[10:11], 0, v[174:175]
	global_load_lds_dwordx4 v[228:229], off
	s_mov_b32 m0, s68
	s_nop 0
	global_load_lds_dwordx4 v[230:231], off
	s_cmp_lg_u32 s86, 1
	s_cbranch_scc1 .Lpeel2_mx1
	s_waitcnt vmcnt(8)
; #define PG8_STAGE(bufoff, gbase, voff) do { _Pragma("unroll") for (int _i = 0; _i < 2; ++_i) \
;         __builtin_amdgcn_global_load_lds((const unsigned*)((const char*)(gbase) + (voff)[_i]), (PG8_LAS unsigned*)(lds + (bufoff) + ldsw + _i * 8192), 16, 0, 0); } while (0)
; #define PG8_LDA(dst, b, h) do { _Pragma("unroll") for (int m = 0; m < 4; ++m) _Pragma("unroll") for (int k = 0; k < 2; ++k) dst[m][k] = *(const PG8_LAS bf16x8*)(lds + PG8_SA(b, h) + aoff + m * 2048 + k * 1024); } while (0)
; #define PG8_LDB(dst, b, h) do { _Pragma("unroll") for (int n = 0; n < 2; ++n) _Pragma("unroll") for (int k = 0; k < 2; ++k) dst[n][k] = *(const PG8_LAS bf16x8*)(lds + PG8_SB(b, h) + boff + n * 2048 + k * 1024); } while (0)
; #define PG8_MMA(ai, bj, At, Bt) do { __builtin_amdgcn_s_setprio(1); _Pragma("unroll") for (int m = 0; m < 4; ++m) _Pragma("unroll") for (int n = 0; n < 2; ++n) _Pragma("unroll") for (int k = 0; k < 2; ++k) \
;         acc[ai][bj][m][n] = __builtin_amdgcn_mfma_f32_16x16x32_bf16(Bt[n][k], At[m][k], acc[ai][bj][m][n], 0, 0, 0); __builtin_amdgcn_s_setprio(0); } while (0)
; #define PG8_WAIT_V(n) asm volatile("s_waitcnt vmcnt(" #n ")" ::: "memory")
; #define PG8_WAIT_L(n) asm volatile("s_waitcnt lgkmcnt(" #n ")" ::: "memory")
; #define PG8_BAR __builtin_amdgcn_s_barrier()
; #define PG8_SCHED __builtin_amdgcn_sched_barrier(0)
; template <class Epi, class Sched, bool ALIGN_EPI = false, bool SP2 = false>
; __device__ __forceinline__ void gemm_phase(PG8_LAS unsigned char* lds, const Gemm g, const Sched& S, const Epi& E, const int tid_) {
;     ...
;             PG8_WAIT_V(8); PG8_WAIT_L(0); PG8_BAR; PG8_MMA(1, 0, At, B0); PG8_MMA(1, 1, At, B1); PG8_BAR; PG8_SCHED;
;             PG8_LDB(B0, 1, 0); PG8_LDB(B1, 1, 1); PG8_SCHED; PG8_LDA(At, 1, 0); PG8_STAGE(PG8_SA(0, 1), a2 + hstep, voffA);
;             PG8_WAIT_V(8); PG8_WAIT_L(0); PG8_BAR; PG8_MMA(0, 0, At, B0); PG8_MMA(0, 1, At, B1); PG8_BAR; PG8_SCHED;
.Lpeel2_mx1:
	s_waitcnt lgkmcnt(0)
	s_barrier
	s_setprio 1
	s_waitcnt lgkmcnt(0)
	v_mfma_f32_16x16x32_bf16 v[80:83], v[12:15], v[164:167], 0
	v_mfma_f32_16x16x32_bf16 v[76:79], v[36:39], v[164:167], 0
	v_mfma_f32_16x16x32_bf16 v[64:67], v[12:15], v[198:201], 0
	v_mfma_f32_16x16x32_bf16 v[60:63], v[36:39], v[198:201], 0
	v_mfma_f32_16x16x32_bf16 v[48:51], v[12:15], v[206:209], 0
	v_mfma_f32_16x16x32_bf16 v[44:47], v[36:39], v[206:209], 0
	v_mfma_f32_16x16x32_bf16 v[12:15], v[12:15], v[214:217], 0
	v_mfma_f32_16x16x32_bf16 v[80:83], v[16:19], v[168:171], v[80:83]
	v_mfma_f32_16x16x32_bf16 v[76:79], v[40:43], v[168:171], v[76:79]
	v_mfma_f32_16x16x32_bf16 v[64:67], v[16:19], v[202:205], v[64:67]
	v_mfma_f32_16x16x32_bf16 v[60:63], v[40:43], v[202:205], v[60:63]
	v_mfma_f32_16x16x32_bf16 v[48:51], v[16:19], v[210:213], v[48:51]
	v_mfma_f32_16x16x32_bf16 v[44:47], v[40:43], v[210:213], v[44:47]
	v_mfma_f32_16x16x32_bf16 v[12:15], v[16:19], v[218:221], v[12:15]
	v_mfma_f32_16x16x32_bf16 v[16:19], v[36:39], v[214:217], 0
	v_mfma_f32_16x16x32_bf16 v[16:19], v[40:43], v[218:221], v[16:19]
	s_setprio 0
	s_setprio 1
	v_mfma_f32_16x16x32_bf16 v[20:23], v[148:151], v[164:167], 0
	v_mfma_f32_16x16x32_bf16 v[36:39], v[152:155], v[168:171], v[20:23]
	v_mfma_f32_16x16x32_bf16 v[20:23], v[156:159], v[164:167], 0
	v_mfma_f32_16x16x32_bf16 v[40:43], v[160:163], v[168:171], v[20:23]
	v_mfma_f32_16x16x32_bf16 v[20:23], v[148:151], v[198:201], 0
	v_mfma_f32_16x16x32_bf16 v[56:59], v[152:155], v[202:205], v[20:23]
	v_mfma_f32_16x16x32_bf16 v[20:23], v[156:159], v[198:201], 0
	v_mfma_f32_16x16x32_bf16 v[52:55], v[160:163], v[202:205], v[20:23]
	v_mfma_f32_16x16x32_bf16 v[20:23], v[148:151], v[206:209], 0
	v_mfma_f32_16x16x32_bf16 v[32:35], v[152:155], v[210:213], v[20:23]
	v_mfma_f32_16x16x32_bf16 v[20:23], v[156:159], v[206:209], 0
	v_mfma_f32_16x16x32_bf16 v[8:11], v[148:151], v[214:217], 0
	v_mfma_f32_16x16x32_bf16 v[4:7], v[156:159], v[214:217], 0
	v_mfma_f32_16x16x32_bf16 v[28:31], v[160:163], v[210:213], v[20:23]
	v_mfma_f32_16x16x32_bf16 v[8:11], v[152:155], v[218:221], v[8:11]
	v_mfma_f32_16x16x32_bf16 v[4:7], v[160:163], v[218:221], v[4:7]
	s_setprio 0
	s_barrier
	v_add_u32_e32 v72, s71, v197
	v_add_u32_e32 v160, s76, v197
	ds_read_b128 v[20:23], v72
	ds_read_b128 v[24:27], v72 offset:1024
	ds_read_b128 v[68:71], v72 offset:2048
	ds_read_b128 v[72:75], v72 offset:3072
	ds_read_b128 v[148:151], v160
	ds_read_b128 v[152:155], v160 offset:1024
	ds_read_b128 v[156:159], v160 offset:2048
	ds_read_b128 v[160:163], v160 offset:3072
	s_add_u32 s10, s10, s34
	s_addc_u32 s11, s11, s35
	s_mov_b32 m0, s69
	v_lshl_add_u64 v[232:233], s[10:11], 0, v[0:1]
	ds_read_b128 v[164:167], v238 offset:32768
	ds_read_b128 v[168:171], v238 offset:33792
	ds_read_b128 v[198:201], v238 offset:34816
	ds_read_b128 v[202:205], v238 offset:35840
	ds_read_b128 v[206:209], v238 offset:36864
	ds_read_b128 v[210:213], v238 offset:37888
	ds_read_b128 v[214:217], v238 offset:38912
	ds_read_b128 v[218:221], v238 offset:39936
	global_load_lds_dwordx4 v[232:233], off
	v_lshl_add_u64 v[232:233], s[10:11], 0, v[174:175]
	s_mov_b32 m0, s70
	s_nop 0
	global_load_lds_dwordx4 v[232:233], off
	s_waitcnt vmcnt(8)
	s_waitcnt lgkmcnt(0)
	s_barrier
	s_setprio 1
	s_waitcnt lgkmcnt(0)
	v_mfma_f32_16x16x32_bf16 v[144:147], v[20:23], v[164:167], v[144:147]
	v_mfma_f32_16x16x32_bf16 v[140:143], v[68:71], v[164:167], v[140:143]
	v_mfma_f32_16x16x32_bf16 v[128:131], v[20:23], v[198:201], v[128:131]
	v_mfma_f32_16x16x32_bf16 v[124:127], v[68:71], v[198:201], v[124:127]
	v_mfma_f32_16x16x32_bf16 v[112:115], v[20:23], v[206:209], v[112:115]
	v_mfma_f32_16x16x32_bf16 v[108:111], v[68:71], v[206:209], v[108:111]
	v_mfma_f32_16x16x32_bf16 v[96:99], v[20:23], v[214:217], v[96:99]
	v_mfma_f32_16x16x32_bf16 v[92:95], v[68:71], v[214:217], v[92:95]
	v_mfma_f32_16x16x32_bf16 v[144:147], v[24:27], v[168:171], v[144:147]
	v_mfma_f32_16x16x32_bf16 v[140:143], v[72:75], v[168:171], v[140:143]
	v_mfma_f32_16x16x32_bf16 v[128:131], v[24:27], v[202:205], v[128:131]
	v_mfma_f32_16x16x32_bf16 v[124:127], v[72:75], v[202:205], v[124:127]
	v_mfma_f32_16x16x32_bf16 v[112:115], v[24:27], v[210:213], v[112:115]
	v_mfma_f32_16x16x32_bf16 v[108:111], v[72:75], v[210:213], v[108:111]
	v_mfma_f32_16x16x32_bf16 v[96:99], v[24:27], v[218:221], v[96:99]
	v_mfma_f32_16x16x32_bf16 v[92:95], v[72:75], v[218:221], v[92:95]
	s_setprio 0
	s_setprio 1
	v_mfma_f32_16x16x32_bf16 v[136:139], v[148:151], v[164:167], v[136:139]
	v_mfma_f32_16x16x32_bf16 v[132:135], v[156:159], v[164:167], v[132:135]
	v_mfma_f32_16x16x32_bf16 v[120:123], v[148:151], v[198:201], v[120:123]
	v_mfma_f32_16x16x32_bf16 v[116:119], v[156:159], v[198:201], v[116:119]
	v_mfma_f32_16x16x32_bf16 v[104:107], v[148:151], v[206:209], v[104:107]
	v_mfma_f32_16x16x32_bf16 v[100:103], v[156:159], v[206:209], v[100:103]
	v_mfma_f32_16x16x32_bf16 v[88:91], v[148:151], v[214:217], v[88:91]
	v_mfma_f32_16x16x32_bf16 v[84:87], v[156:159], v[214:217], v[84:87]
	v_mfma_f32_16x16x32_bf16 v[136:139], v[152:155], v[168:171], v[136:139]
	v_mfma_f32_16x16x32_bf16 v[132:135], v[160:163], v[168:171], v[132:135]
	v_mfma_f32_16x16x32_bf16 v[120:123], v[152:155], v[202:205], v[120:123]
	v_mfma_f32_16x16x32_bf16 v[116:119], v[160:163], v[202:205], v[116:119]
	v_mfma_f32_16x16x32_bf16 v[104:107], v[152:155], v[210:213], v[104:107]
	v_mfma_f32_16x16x32_bf16 v[100:103], v[160:163], v[210:213], v[100:103]
	v_mfma_f32_16x16x32_bf16 v[88:91], v[152:155], v[218:221], v[88:91]
	v_mfma_f32_16x16x32_bf16 v[84:87], v[160:163], v[218:221], v[84:87]
	s_setprio 0
	s_barrier
; #define PG8_STAGE(bufoff, gbase, voff) do { _Pragma("unroll") for (int _i = 0; _i < 2; ++_i) \
;         __builtin_amdgcn_global_load_lds((const unsigned*)((const char*)(gbase) + (voff)[_i]), (PG8_LAS unsigned*)(lds + (bufoff) + ldsw + _i * 8192), 16, 0, 0); } while (0)
; #define PG8_LDA(dst, b, h) do { _Pragma("unroll") for (int m = 0; m < 4; ++m) _Pragma("unroll") for (int k = 0; k < 2; ++k) dst[m][k] = *(const PG8_LAS bf16x8*)(lds + PG8_SA(b, h) + aoff + m * 2048 + k * 1024); } while (0)
; #define PG8_MMA(ai, bj, At, Bt) do { __builtin_amdgcn_s_setprio(1); _Pragma("unroll") for (int m = 0; m < 4; ++m) _Pragma("unroll") for (int n = 0; n < 2; ++n) _Pragma("unroll") for (int k = 0; k < 2; ++k) \
;         acc[ai][bj][m][n] = __builtin_amdgcn_mfma_f32_16x16x32_bf16(Bt[n][k], At[m][k], acc[ai][bj][m][n], 0, 0, 0); __builtin_amdgcn_s_setprio(0); } while (0)
; #define PG8_WAIT_V(n) asm volatile("s_waitcnt vmcnt(" #n ")" ::: "memory")
; #define PG8_WAIT_L(n) asm volatile("s_waitcnt lgkmcnt(" #n ")" ::: "memory")
; #define PG8_BAR __builtin_amdgcn_s_barrier()
; #define PG8_SCHED __builtin_amdgcn_sched_barrier(0)
; template <class Epi, class Sched, bool ALIGN_EPI = false, bool SP2 = false>
; __device__ __forceinline__ void gemm_phase(PG8_LAS unsigned char* lds, const Gemm g, const Sched& S, const Epi& E, const int tid_) {
;     ...
;         for (int t = 0; t < nt; t += 2) {
;     ...
;             PG8_LDA(At, 1, 1); PG8_STAGE(PG8_SB(1, 0), b3, voffB); PG8_STAGE(PG8_SB(1, 1), b3 + hstepB, voffB); PG8_STAGE(PG8_SA(1, 0), a3, voffA);
;             PG8_WAIT_V(8); PG8_WAIT_L(0); PG8_BAR; PG8_MMA(1, 0, At, B0); PG8_MMA(1, 1, At, B1); PG8_BAR; PG8_SCHED;
	s_mov_b32 m0, s72
	v_lshl_add_u64 v[194:195], v[194:195], 0, s[96:97]
	ds_read_b128 v[164:167], v238 offset:49152
	ds_read_b128 v[168:171], v238 offset:50176
	ds_read_b128 v[198:201], v238 offset:51200
	ds_read_b128 v[202:205], v238 offset:52224
	ds_read_b128 v[206:209], v238 offset:53248
	ds_read_b128 v[210:213], v238 offset:54272
	ds_read_b128 v[214:217], v238 offset:55296
	ds_read_b128 v[218:221], v238 offset:56320
	global_load_lds_dwordx4 v[194:195], off
	v_lshl_add_u64 v[194:195], v[222:223], 0, s[96:97]
	s_mov_b32 m0, s73
	s_nop 0
	global_load_lds_dwordx4 v[194:195], off
	v_lshl_add_u64 v[194:195], v[224:225], 0, s[96:97]
	s_mov_b32 m0, s77
	s_nop 0
	global_load_lds_dwordx4 v[194:195], off
	v_lshl_add_u64 v[194:195], v[226:227], 0, s[96:97]
	s_mov_b32 m0, s80
	s_nop 0
	global_load_lds_dwordx4 v[194:195], off
	v_lshl_add_u64 v[194:195], v[228:229], 0, s[96:97]
	s_mov_b32 m0, s74
	s_nop 0
	global_load_lds_dwordx4 v[194:195], off
	v_lshl_add_u64 v[194:195], v[230:231], 0, s[96:97]
	s_mov_b32 m0, s75
	s_nop 0
	global_load_lds_dwordx4 v[194:195], off
	s_waitcnt vmcnt(8)
	s_waitcnt lgkmcnt(0)
	s_barrier
	s_setprio 1
	s_waitcnt lgkmcnt(0)
	v_mfma_f32_16x16x32_bf16 v[80:83], v[20:23], v[164:167], v[80:83]
	v_mfma_f32_16x16x32_bf16 v[64:67], v[20:23], v[198:201], v[64:67]
	v_mfma_f32_16x16x32_bf16 v[48:51], v[20:23], v[206:209], v[48:51]
	v_mfma_f32_16x16x32_bf16 v[12:15], v[20:23], v[214:217], v[12:15]
	v_mfma_f32_16x16x32_bf16 v[80:83], v[24:27], v[168:171], v[80:83]
	v_mfma_f32_16x16x32_bf16 v[76:79], v[68:71], v[164:167], v[76:79]
	v_mfma_f32_16x16x32_bf16 v[64:67], v[24:27], v[202:205], v[64:67]
	v_mfma_f32_16x16x32_bf16 v[60:63], v[68:71], v[198:201], v[60:63]
	v_mfma_f32_16x16x32_bf16 v[48:51], v[24:27], v[210:213], v[48:51]
	v_mfma_f32_16x16x32_bf16 v[44:47], v[68:71], v[206:209], v[44:47]
	v_mfma_f32_16x16x32_bf16 v[24:27], v[24:27], v[218:221], v[12:15]
	v_mfma_f32_16x16x32_bf16 v[12:15], v[68:71], v[214:217], v[16:19]
	v_mfma_f32_16x16x32_bf16 v[76:79], v[72:75], v[168:171], v[76:79]
	v_mfma_f32_16x16x32_bf16 v[60:63], v[72:75], v[202:205], v[60:63]
	v_mfma_f32_16x16x32_bf16 v[44:47], v[72:75], v[210:213], v[44:47]
	v_mfma_f32_16x16x32_bf16 v[20:23], v[72:75], v[218:221], v[12:15]
	s_setprio 0
	s_setprio 1
	v_mfma_f32_16x16x32_bf16 v[12:15], v[148:151], v[164:167], v[36:39]
	v_mfma_f32_16x16x32_bf16 v[72:75], v[152:155], v[168:171], v[12:15]
	v_mfma_f32_16x16x32_bf16 v[12:15], v[156:159], v[164:167], v[40:43]
	v_mfma_f32_16x16x32_bf16 v[68:71], v[160:163], v[168:171], v[12:15]
	v_mfma_f32_16x16x32_bf16 v[12:15], v[148:151], v[198:201], v[56:59]
	v_mfma_f32_16x16x32_bf16 v[56:59], v[152:155], v[202:205], v[12:15]
	v_mfma_f32_16x16x32_bf16 v[12:15], v[156:159], v[198:201], v[52:55]
	v_mfma_f32_16x16x32_bf16 v[52:55], v[160:163], v[202:205], v[12:15]
	v_mfma_f32_16x16x32_bf16 v[12:15], v[148:151], v[206:209], v[32:35]
	v_mfma_f32_16x16x32_bf16 v[32:35], v[152:155], v[210:213], v[12:15]
	v_mfma_f32_16x16x32_bf16 v[12:15], v[156:159], v[206:209], v[28:31]
	v_mfma_f32_16x16x32_bf16 v[8:11], v[148:151], v[214:217], v[8:11]
	v_mfma_f32_16x16x32_bf16 v[4:7], v[156:159], v[214:217], v[4:7]
	v_mfma_f32_16x16x32_bf16 v[28:31], v[160:163], v[210:213], v[12:15]
	v_mfma_f32_16x16x32_bf16 v[8:11], v[152:155], v[218:221], v[8:11]
	v_mfma_f32_16x16x32_bf16 v[4:7], v[160:163], v[218:221], v[4:7]
	s_setprio 0
	s_barrier
	s_add_u32 s8, s8, 0x100
	s_addc_u32 s9, s9, 0
	s_add_u32 s2, s2, 0x100
	s_addc_u32 s3, s3, 0
	s_cmp_ge_u32 s12, s81
	s_mov_b32 s10, s12

; #define PG8_STAGE(bufoff, gbase, voff) do { _Pragma("unroll") for (int _i = 0; _i < 2; ++_i) \
;         __builtin_amdgcn_global_load_lds((const unsigned*)((const char*)(gbase) + (voff)[_i]), (PG8_LAS unsigned*)(lds + (bufoff) + ldsw + _i * 8192), 16, 0, 0); } while (0)
; #define PG8_LDA(dst, b, h) do { _Pragma("unroll") for (int m = 0; m < 4; ++m) _Pragma("unroll") for (int k = 0; k < 2; ++k) dst[m][k] = *(const PG8_LAS bf16x8*)(lds + PG8_SA(b, h) + aoff + m * 2048 + k * 1024); } while (0)
; #define PG8_LDB(dst, b, h) do { _Pragma("unroll") for (int n = 0; n < 2; ++n) _Pragma("unroll") for (int k = 0; k < 2; ++k) dst[n][k] = *(const PG8_LAS bf16x8*)(lds + PG8_SB(b, h) + boff + n * 2048 + k * 1024); } while (0)
; #define PG8_MMA(ai, bj, At, Bt) do { __builtin_amdgcn_s_setprio(1); _Pragma("unroll") for (int m = 0; m < 4; ++m) _Pragma("unroll") for (int n = 0; n < 2; ++n) _Pragma("unroll") for (int k = 0; k < 2; ++k) \
;         acc[ai][bj][m][n] = __builtin_amdgcn_mfma_f32_16x16x32_bf16(Bt[n][k], At[m][k], acc[ai][bj][m][n], 0, 0, 0); __builtin_amdgcn_s_setprio(0); } while (0)
; #define PG8_WAIT_V(n) asm volatile("s_waitcnt vmcnt(" #n ")" ::: "memory")
; #define PG8_WAIT_L(n) asm volatile("s_waitcnt lgkmcnt(" #n ")" ::: "memory")
; #define PG8_BAR __builtin_amdgcn_s_barrier()
; #define PG8_SCHED __builtin_amdgcn_sched_barrier(0)
; template <class Epi, class Sched, bool ALIGN_EPI = false, bool SP2 = false>
; __device__ __forceinline__ void gemm_phase(PG8_LAS unsigned char* lds, const Gemm g, const Sched& S, const Epi& E, const int tid_) {
;     ...
;             const bool last = (t == nt - 2);
;             const char* a1 = cA + (size_t)(t + 1) * kstep;
;             const char* a2 = last ? nA : cA + (size_t)(t + 2) * kstep; const char* b2 = last ? nB : cB + (size_t)(t + 2) * kstep;
;             const char* a3 = a2 + kstep; const char* b3 = b2 + kstep;
;             if (last && has_next) S.a_ready(nxt);
;             if constexpr (SP2) {
;             PG8_LDB(B0, 0, 0); PG8_LDB(B1, 0, 1); PG8_SCHED; PG8_LDA(At, 0, 0); PG8_STAGE(PG8_SA(1, 1), a1 + hstep, voffA);
;             PG8_WAIT_V(8); PG8_WAIT_L(0); PG8_BAR; PG8_MMA(0, 0, At, B0); PG8_MMA(0, 1, At, B1); PG8_BAR; PG8_SCHED;
;             PG8_LDA(At, 0, 1); PG8_STAGE(PG8_SB(0, 0), b2, voffB); PG8_STAGE(PG8_SB(0, 1), b2 + hstepB, voffB); PG8_STAGE(PG8_SA(0, 0), a2, voffA);
.LBB0_527:
	s_add_u32 s12, s48, 0x80
	s_addc_u32 s13, s49, 0
	s_add_u32 s2, s46, 0x100
	s_addc_u32 s3, s47, 0
	s_mov_b32 s14, 0
	s_waitcnt lgkmcnt(0)
	v_add_u32_e32 v56, s53, v214
	v_add_u32_e32 v160, s56, v214
	ds_read_b128 v[36:39], v56
	ds_read_b128 v[40:43], v56 offset:1024
	ds_read_b128 v[48:51], v56 offset:2048
	ds_read_b128 v[56:59], v56 offset:3072
	ds_read_b128 v[148:151], v160
	ds_read_b128 v[152:155], v160 offset:1024
	ds_read_b128 v[156:159], v160 offset:2048
	ds_read_b128 v[160:163], v160 offset:3072
	s_add_i32 s46, s14, 2
	s_add_u32 s47, s12, 0x80
	s_addc_u32 s15, s13, 0
	s_cmp_eq_u32 s74, s14
	s_cselect_b32 s14, s42, s47
	s_cselect_b32 s15, s43, s15
	s_cselect_b32 s49, s45, s3
	s_cselect_b32 s48, s44, s2
	v_lshl_add_u64 v[212:213], s[12:13], 0, v[192:193]
	s_add_i32 m0, s59, 0xc000
	ds_read_b128 v[164:167], v216
	ds_read_b128 v[168:171], v216 offset:1024
	ds_read_b128 v[172:175], v216 offset:2048
	ds_read_b128 v[176:179], v216 offset:3072
	ds_read_b128 v[196:199], v216 offset:4096
	ds_read_b128 v[200:203], v216 offset:5120
	ds_read_b128 v[204:207], v216 offset:6144
	ds_read_b128 v[208:211], v216 offset:7168
	global_load_lds_dwordx4 v[212:213], off
	v_lshl_add_u64 v[212:213], s[12:13], 0, v[194:195]
	s_add_i32 m0, s59, 0xe000
	s_nop 0
	global_load_lds_dwordx4 v[212:213], off
	s_cmp_lg_u32 s71, 1
	s_cbranch_scc1 .Lpeel2_rs0
	s_waitcnt vmcnt(8)
.Lpeel2_rs0:
	s_waitcnt lgkmcnt(0)
	s_barrier
	s_setprio 1
	s_waitcnt lgkmcnt(0)
	v_mfma_f32_16x16x32_bf16 v[144:147], v[36:39], v[164:167], 0
	v_mfma_f32_16x16x32_bf16 v[140:143], v[48:51], v[164:167], 0
	v_mfma_f32_16x16x32_bf16 v[128:131], v[36:39], v[172:175], 0
	v_mfma_f32_16x16x32_bf16 v[124:127], v[48:51], v[172:175], 0
	v_mfma_f32_16x16x32_bf16 v[112:115], v[36:39], v[196:199], 0
	v_mfma_f32_16x16x32_bf16 v[108:111], v[48:51], v[196:199], 0
	v_mfma_f32_16x16x32_bf16 v[96:99], v[36:39], v[204:207], 0
	v_mfma_f32_16x16x32_bf16 v[92:95], v[48:51], v[204:207], 0
	v_mfma_f32_16x16x32_bf16 v[144:147], v[40:43], v[168:171], v[144:147]
	v_mfma_f32_16x16x32_bf16 v[140:143], v[56:59], v[168:171], v[140:143]
	v_mfma_f32_16x16x32_bf16 v[128:131], v[40:43], v[176:179], v[128:131]
	v_mfma_f32_16x16x32_bf16 v[124:127], v[56:59], v[176:179], v[124:127]
	v_mfma_f32_16x16x32_bf16 v[112:115], v[40:43], v[200:203], v[112:115]
	v_mfma_f32_16x16x32_bf16 v[108:111], v[56:59], v[200:203], v[108:111]
	v_mfma_f32_16x16x32_bf16 v[96:99], v[40:43], v[208:211], v[96:99]
	v_mfma_f32_16x16x32_bf16 v[92:95], v[56:59], v[208:211], v[92:95]
	s_setprio 0
	s_setprio 1
	v_mfma_f32_16x16x32_bf16 v[136:139], v[148:151], v[164:167], 0
	v_mfma_f32_16x16x32_bf16 v[132:135], v[156:159], v[164:167], 0
	v_mfma_f32_16x16x32_bf16 v[120:123], v[148:151], v[172:175], 0
	v_mfma_f32_16x16x32_bf16 v[116:119], v[156:159], v[172:175], 0
	v_mfma_f32_16x16x32_bf16 v[104:107], v[148:151], v[196:199], 0
	v_mfma_f32_16x16x32_bf16 v[100:103], v[156:159], v[196:199], 0
	v_mfma_f32_16x16x32_bf16 v[88:91], v[148:151], v[204:207], 0
	v_mfma_f32_16x16x32_bf16 v[84:87], v[156:159], v[204:207], 0
	v_mfma_f32_16x16x32_bf16 v[136:139], v[152:155], v[168:171], v[136:139]
	v_mfma_f32_16x16x32_bf16 v[132:135], v[160:163], v[168:171], v[132:135]
	v_mfma_f32_16x16x32_bf16 v[120:123], v[152:155], v[176:179], v[120:123]
	v_mfma_f32_16x16x32_bf16 v[116:119], v[160:163], v[176:179], v[116:119]
	v_mfma_f32_16x16x32_bf16 v[104:107], v[152:155], v[200:203], v[104:107]
	v_mfma_f32_16x16x32_bf16 v[100:103], v[160:163], v[200:203], v[100:103]
	v_mfma_f32_16x16x32_bf16 v[88:91], v[152:155], v[208:211], v[88:91]
	v_mfma_f32_16x16x32_bf16 v[84:87], v[160:163], v[208:211], v[84:87]
	s_setprio 0
	s_barrier
	s_mov_b32 m0, s54
	v_lshl_add_u64 v[212:213], s[48:49], 0, v[2:3]
	v_lshl_add_u64 v[218:219], s[48:49], 0, v[190:191]
	s_add_u32 s48, s48, s52
	ds_read_b128 v[164:167], v216 offset:16384
	ds_read_b128 v[168:171], v216 offset:17408
	ds_read_b128 v[172:175], v216 offset:18432
	ds_read_b128 v[176:179], v216 offset:19456
	ds_read_b128 v[196:199], v216 offset:20480
	ds_read_b128 v[200:203], v216 offset:21504
	ds_read_b128 v[204:207], v216 offset:22528
	ds_read_b128 v[208:211], v216 offset:23552
	global_load_lds_dwordx4 v[212:213], off
	s_mov_b32 m0, s55
	s_addc_u32 s49, s49, 0
	global_load_lds_dwordx4 v[218:219], off
	v_lshl_add_u64 v[220:221], s[48:49], 0, v[2:3]
	s_mov_b32 m0, s57
	v_lshl_add_u64 v[222:223], s[48:49], 0, v[190:191]
	global_load_lds_dwordx4 v[220:221], off
	s_mov_b32 m0, s58
	v_lshl_add_u64 v[224:225], s[14:15], 0, v[0:1]
	global_load_lds_dwordx4 v[222:223], off
	s_mov_b32 m0, s59
	v_lshl_add_u64 v[226:227], s[14:15], 0, v[188:189]
	global_load_lds_dwordx4 v[224:225], off
	s_mov_b32 m0, s60
	s_nop 0
	global_load_lds_dwordx4 v[226:227], off
	s_cmp_lg_u32 s71, 1
	s_cbranch_scc1 .Lpeel2_rs1
	s_waitcnt vmcnt(8)
; #define PG8_STAGE(bufoff, gbase, voff) do { _Pragma("unroll") for (int _i = 0; _i < 2; ++_i) \
;         __builtin_amdgcn_global_load_lds((const unsigned*)((const char*)(gbase) + (voff)[_i]), (PG8_LAS unsigned*)(lds + (bufoff) + ldsw + _i * 8192), 16, 0, 0); } while (0)
; #define PG8_LDA(dst, b, h) do { _Pragma("unroll") for (int m = 0; m < 4; ++m) _Pragma("unroll") for (int k = 0; k < 2; ++k) dst[m][k] = *(const PG8_LAS bf16x8*)(lds + PG8_SA(b, h) + aoff + m * 2048 + k * 1024); } while (0)
; #define PG8_LDB(dst, b, h) do { _Pragma("unroll") for (int n = 0; n < 2; ++n) _Pragma("unroll") for (int k = 0; k < 2; ++k) dst[n][k] = *(const PG8_LAS bf16x8*)(lds + PG8_SB(b, h) + boff + n * 2048 + k * 1024); } while (0)
; #define PG8_MMA(ai, bj, At, Bt) do { __builtin_amdgcn_s_setprio(1); _Pragma("unroll") for (int m = 0; m < 4; ++m) _Pragma("unroll") for (int n = 0; n < 2; ++n) _Pragma("unroll") for (int k = 0; k < 2; ++k) \
;         acc[ai][bj][m][n] = __builtin_amdgcn_mfma_f32_16x16x32_bf16(Bt[n][k], At[m][k], acc[ai][bj][m][n], 0, 0, 0); __builtin_amdgcn_s_setprio(0); } while (0)
; #define PG8_WAIT_V(n) asm volatile("s_waitcnt vmcnt(" #n ")" ::: "memory")
; #define PG8_WAIT_L(n) asm volatile("s_waitcnt lgkmcnt(" #n ")" ::: "memory")
; #define PG8_BAR __builtin_amdgcn_s_barrier()
; #define PG8_SCHED __builtin_amdgcn_sched_barrier(0)
; template <class Epi, class Sched, bool ALIGN_EPI = false, bool SP2 = false>
; __device__ __forceinline__ void gemm_phase(PG8_LAS unsigned char* lds, const Gemm g, const Sched& S, const Epi& E, const int tid_) {
;     ...
;             PG8_WAIT_V(8); PG8_WAIT_L(0); PG8_BAR; PG8_MMA(1, 0, At, B0); PG8_MMA(1, 1, At, B1); PG8_BAR; PG8_SCHED;
;             PG8_LDB(B0, 1, 0); PG8_LDB(B1, 1, 1); PG8_SCHED; PG8_LDA(At, 1, 0); PG8_STAGE(PG8_SA(0, 1), a2 + hstep, voffA);
;             PG8_WAIT_V(8); PG8_WAIT_L(0); PG8_BAR; PG8_MMA(0, 0, At, B0); PG8_MMA(0, 1, At, B1); PG8_BAR; PG8_SCHED;
.Lpeel2_rs1:
	s_waitcnt lgkmcnt(0)
	s_barrier
	s_setprio 1
	s_waitcnt lgkmcnt(0)
	v_mfma_f32_16x16x32_bf16 v[80:83], v[36:39], v[164:167], 0
	v_mfma_f32_16x16x32_bf16 v[76:79], v[48:51], v[164:167], 0
	v_mfma_f32_16x16x32_bf16 v[64:67], v[36:39], v[172:175], 0
	v_mfma_f32_16x16x32_bf16 v[60:63], v[48:51], v[172:175], 0
	v_mfma_f32_16x16x32_bf16 v[32:35], v[36:39], v[196:199], 0
	v_mfma_f32_16x16x32_bf16 v[28:31], v[48:51], v[196:199], 0
	v_mfma_f32_16x16x32_bf16 v[16:19], v[36:39], v[204:207], 0
	v_mfma_f32_16x16x32_bf16 v[12:15], v[48:51], v[204:207], 0
	v_mfma_f32_16x16x32_bf16 v[80:83], v[40:43], v[168:171], v[80:83]
	v_mfma_f32_16x16x32_bf16 v[76:79], v[56:59], v[168:171], v[76:79]
	v_mfma_f32_16x16x32_bf16 v[64:67], v[40:43], v[176:179], v[64:67]
	v_mfma_f32_16x16x32_bf16 v[60:63], v[56:59], v[176:179], v[60:63]
	v_mfma_f32_16x16x32_bf16 v[32:35], v[40:43], v[200:203], v[32:35]
	v_mfma_f32_16x16x32_bf16 v[28:31], v[56:59], v[200:203], v[28:31]
	v_mfma_f32_16x16x32_bf16 v[16:19], v[40:43], v[208:211], v[16:19]
	v_mfma_f32_16x16x32_bf16 v[12:15], v[56:59], v[208:211], v[12:15]
	s_setprio 0
	s_setprio 1
	v_mfma_f32_16x16x32_bf16 v[44:47], v[156:159], v[172:175], 0
	v_mfma_f32_16x16x32_bf16 v[24:27], v[148:151], v[196:199], 0
	v_mfma_f32_16x16x32_bf16 v[20:23], v[156:159], v[196:199], 0
	v_mfma_f32_16x16x32_bf16 v[8:11], v[148:151], v[204:207], 0
	v_mfma_f32_16x16x32_bf16 v[4:7], v[156:159], v[204:207], 0
	v_mfma_f32_16x16x32_bf16 v[36:39], v[148:151], v[164:167], 0
	v_mfma_f32_16x16x32_bf16 v[40:43], v[156:159], v[164:167], 0
	v_mfma_f32_16x16x32_bf16 v[48:51], v[148:151], v[172:175], 0
	v_mfma_f32_16x16x32_bf16 v[44:47], v[160:163], v[176:179], v[44:47]
	v_mfma_f32_16x16x32_bf16 v[24:27], v[152:155], v[200:203], v[24:27]
	v_mfma_f32_16x16x32_bf16 v[20:23], v[160:163], v[200:203], v[20:23]
	v_mfma_f32_16x16x32_bf16 v[8:11], v[152:155], v[208:211], v[8:11]
	v_mfma_f32_16x16x32_bf16 v[4:7], v[160:163], v[208:211], v[4:7]
	v_mfma_f32_16x16x32_bf16 v[36:39], v[152:155], v[168:171], v[36:39]
	v_mfma_f32_16x16x32_bf16 v[40:43], v[160:163], v[168:171], v[40:43]
	v_mfma_f32_16x16x32_bf16 v[48:51], v[152:155], v[176:179], v[48:51]
	s_setprio 0
	s_barrier
	v_add_u32_e32 v72, s63, v214
	v_add_u32_e32 v160, s68, v214
	ds_read_b128 v[52:55], v72
	ds_read_b128 v[56:59], v72 offset:1024
	ds_read_b128 v[68:71], v72 offset:2048
	ds_read_b128 v[72:75], v72 offset:3072
	ds_read_b128 v[148:151], v160
	ds_read_b128 v[152:155], v160 offset:1024
	ds_read_b128 v[156:159], v160 offset:2048
	ds_read_b128 v[160:163], v160 offset:3072
	s_add_u32 s14, s14, s24
	s_addc_u32 s15, s15, 0
	s_mov_b32 m0, s61
	v_lshl_add_u64 v[228:229], s[14:15], 0, v[0:1]
	ds_read_b128 v[164:167], v216 offset:32768
	ds_read_b128 v[168:171], v216 offset:33792
	ds_read_b128 v[172:175], v216 offset:34816
	ds_read_b128 v[176:179], v216 offset:35840
	ds_read_b128 v[196:199], v216 offset:36864
	ds_read_b128 v[200:203], v216 offset:37888
	ds_read_b128 v[204:207], v216 offset:38912
	ds_read_b128 v[208:211], v216 offset:39936
	global_load_lds_dwordx4 v[228:229], off
	v_lshl_add_u64 v[228:229], s[14:15], 0, v[188:189]
	s_mov_b32 m0, s62
	s_nop 0
	global_load_lds_dwordx4 v[228:229], off
	s_waitcnt vmcnt(8)
	s_waitcnt lgkmcnt(0)
	s_barrier
	s_setprio 1
	s_waitcnt lgkmcnt(0)
	v_mfma_f32_16x16x32_bf16 v[144:147], v[52:55], v[164:167], v[144:147]
	v_mfma_f32_16x16x32_bf16 v[140:143], v[68:71], v[164:167], v[140:143]
	v_mfma_f32_16x16x32_bf16 v[128:131], v[52:55], v[172:175], v[128:131]
	v_mfma_f32_16x16x32_bf16 v[124:127], v[68:71], v[172:175], v[124:127]
	v_mfma_f32_16x16x32_bf16 v[112:115], v[52:55], v[196:199], v[112:115]
	v_mfma_f32_16x16x32_bf16 v[108:111], v[68:71], v[196:199], v[108:111]
	v_mfma_f32_16x16x32_bf16 v[96:99], v[52:55], v[204:207], v[96:99]
	v_mfma_f32_16x16x32_bf16 v[92:95], v[68:71], v[204:207], v[92:95]
	v_mfma_f32_16x16x32_bf16 v[144:147], v[56:59], v[168:171], v[144:147]
	v_mfma_f32_16x16x32_bf16 v[140:143], v[72:75], v[168:171], v[140:143]
	v_mfma_f32_16x16x32_bf16 v[128:131], v[56:59], v[176:179], v[128:131]
	v_mfma_f32_16x16x32_bf16 v[124:127], v[72:75], v[176:179], v[124:127]
	v_mfma_f32_16x16x32_bf16 v[112:115], v[56:59], v[200:203], v[112:115]
	v_mfma_f32_16x16x32_bf16 v[108:111], v[72:75], v[200:203], v[108:111]
	v_mfma_f32_16x16x32_bf16 v[96:99], v[56:59], v[208:211], v[96:99]
	v_mfma_f32_16x16x32_bf16 v[92:95], v[72:75], v[208:211], v[92:95]
	s_setprio 0
	s_setprio 1
	v_mfma_f32_16x16x32_bf16 v[136:139], v[148:151], v[164:167], v[136:139]
	v_mfma_f32_16x16x32_bf16 v[132:135], v[156:159], v[164:167], v[132:135]
	v_mfma_f32_16x16x32_bf16 v[120:123], v[148:151], v[172:175], v[120:123]
	v_mfma_f32_16x16x32_bf16 v[116:119], v[156:159], v[172:175], v[116:119]
	v_mfma_f32_16x16x32_bf16 v[104:107], v[148:151], v[196:199], v[104:107]
	v_mfma_f32_16x16x32_bf16 v[100:103], v[156:159], v[196:199], v[100:103]
	v_mfma_f32_16x16x32_bf16 v[88:91], v[148:151], v[204:207], v[88:91]
	v_mfma_f32_16x16x32_bf16 v[84:87], v[156:159], v[204:207], v[84:87]
	v_mfma_f32_16x16x32_bf16 v[136:139], v[152:155], v[168:171], v[136:139]
	v_mfma_f32_16x16x32_bf16 v[132:135], v[160:163], v[168:171], v[132:135]
	v_mfma_f32_16x16x32_bf16 v[120:123], v[152:155], v[176:179], v[120:123]
	v_mfma_f32_16x16x32_bf16 v[116:119], v[160:163], v[176:179], v[116:119]
	v_mfma_f32_16x16x32_bf16 v[104:107], v[152:155], v[200:203], v[104:107]
	v_mfma_f32_16x16x32_bf16 v[100:103], v[160:163], v[200:203], v[100:103]
	v_mfma_f32_16x16x32_bf16 v[88:91], v[152:155], v[208:211], v[88:91]
	v_mfma_f32_16x16x32_bf16 v[84:87], v[160:163], v[208:211], v[84:87]
	s_setprio 0
	s_barrier
; #define PG8_STAGE(bufoff, gbase, voff) do { _Pragma("unroll") for (int _i = 0; _i < 2; ++_i) \
;         __builtin_amdgcn_global_load_lds((const unsigned*)((const char*)(gbase) + (voff)[_i]), (PG8_LAS unsigned*)(lds + (bufoff) + ldsw + _i * 8192), 16, 0, 0); } while (0)
; #define PG8_LDA(dst, b, h) do { _Pragma("unroll") for (int m = 0; m < 4; ++m) _Pragma("unroll") for (int k = 0; k < 2; ++k) dst[m][k] = *(const PG8_LAS bf16x8*)(lds + PG8_SA(b, h) + aoff + m * 2048 + k * 1024); } while (0)
; #define PG8_MMA(ai, bj, At, Bt) do { __builtin_amdgcn_s_setprio(1); _Pragma("unroll") for (int m = 0; m < 4; ++m) _Pragma("unroll") for (int n = 0; n < 2; ++n) _Pragma("unroll") for (int k = 0; k < 2; ++k) \
;         acc[ai][bj][m][n] = __builtin_amdgcn_mfma_f32_16x16x32_bf16(Bt[n][k], At[m][k], acc[ai][bj][m][n], 0, 0, 0); __builtin_amdgcn_s_setprio(0); } while (0)
; #define PG8_WAIT_V(n) asm volatile("s_waitcnt vmcnt(" #n ")" ::: "memory")
; #define PG8_WAIT_L(n) asm volatile("s_waitcnt lgkmcnt(" #n ")" ::: "memory")
; #define PG8_BAR __builtin_amdgcn_s_barrier()
; #define PG8_SCHED __builtin_amdgcn_sched_barrier(0)
; template <class Epi, class Sched, bool ALIGN_EPI = false, bool SP2 = false>
; __device__ __forceinline__ void gemm_phase(PG8_LAS unsigned char* lds, const Gemm g, const Sched& S, const Epi& E, const int tid_) {
;     ...
;         for (int t = 0; t < nt; t += 2) {
;     ...
;             PG8_LDA(At, 1, 1); PG8_STAGE(PG8_SB(1, 0), b3, voffB); PG8_STAGE(PG8_SB(1, 1), b3 + hstepB, voffB); PG8_STAGE(PG8_SA(1, 0), a3, voffA);
;             PG8_WAIT_V(8); PG8_WAIT_L(0); PG8_BAR; PG8_MMA(1, 0, At, B0); PG8_MMA(1, 1, At, B1); PG8_BAR; PG8_SCHED;
	s_mov_b32 m0, s64
	v_lshl_add_u64 v[212:213], v[212:213], 0, s[96:97]
	ds_read_b128 v[164:167], v216 offset:49152
	ds_read_b128 v[168:171], v216 offset:50176
	ds_read_b128 v[172:175], v216 offset:51200
	ds_read_b128 v[176:179], v216 offset:52224
	ds_read_b128 v[196:199], v216 offset:53248
	ds_read_b128 v[200:203], v216 offset:54272
	ds_read_b128 v[204:207], v216 offset:55296
	ds_read_b128 v[208:211], v216 offset:56320
	global_load_lds_dwordx4 v[212:213], off
	v_lshl_add_u64 v[212:213], v[218:219], 0, s[96:97]
	s_mov_b32 m0, s65
	s_nop 0
	global_load_lds_dwordx4 v[212:213], off
	v_lshl_add_u64 v[212:213], v[220:221], 0, s[96:97]
	s_mov_b32 m0, s69
	s_nop 0
	global_load_lds_dwordx4 v[212:213], off
	v_lshl_add_u64 v[212:213], v[222:223], 0, s[96:97]
	s_mov_b32 m0, s70
	s_nop 0
	global_load_lds_dwordx4 v[212:213], off
	v_lshl_add_u64 v[212:213], v[224:225], 0, s[96:97]
	s_mov_b32 m0, s66
	s_nop 0
	global_load_lds_dwordx4 v[212:213], off
	v_lshl_add_u64 v[212:213], v[226:227], 0, s[96:97]
	s_mov_b32 m0, s67
	s_nop 0
	global_load_lds_dwordx4 v[212:213], off
	s_waitcnt vmcnt(8)
	s_waitcnt lgkmcnt(0)
	s_barrier
	s_setprio 1
	s_waitcnt lgkmcnt(0)
	v_mfma_f32_16x16x32_bf16 v[80:83], v[52:55], v[164:167], v[80:83]
	v_mfma_f32_16x16x32_bf16 v[76:79], v[68:71], v[164:167], v[76:79]
	v_mfma_f32_16x16x32_bf16 v[64:67], v[52:55], v[172:175], v[64:67]
	v_mfma_f32_16x16x32_bf16 v[60:63], v[68:71], v[172:175], v[60:63]
	v_mfma_f32_16x16x32_bf16 v[32:35], v[52:55], v[196:199], v[32:35]
	v_mfma_f32_16x16x32_bf16 v[28:31], v[68:71], v[196:199], v[28:31]
	v_mfma_f32_16x16x32_bf16 v[16:19], v[52:55], v[204:207], v[16:19]
	v_mfma_f32_16x16x32_bf16 v[12:15], v[68:71], v[204:207], v[12:15]
	v_mfma_f32_16x16x32_bf16 v[80:83], v[56:59], v[168:171], v[80:83]
	v_mfma_f32_16x16x32_bf16 v[76:79], v[72:75], v[168:171], v[76:79]
	v_mfma_f32_16x16x32_bf16 v[64:67], v[56:59], v[176:179], v[64:67]
	v_mfma_f32_16x16x32_bf16 v[60:63], v[72:75], v[176:179], v[60:63]
	v_mfma_f32_16x16x32_bf16 v[32:35], v[56:59], v[200:203], v[32:35]
	v_mfma_f32_16x16x32_bf16 v[28:31], v[72:75], v[200:203], v[28:31]
	v_mfma_f32_16x16x32_bf16 v[16:19], v[56:59], v[208:211], v[16:19]
	v_mfma_f32_16x16x32_bf16 v[12:15], v[72:75], v[208:211], v[12:15]
	s_setprio 0
	s_setprio 1
	v_mfma_f32_16x16x32_bf16 v[36:39], v[148:151], v[164:167], v[36:39]
	v_mfma_f32_16x16x32_bf16 v[72:75], v[152:155], v[168:171], v[36:39]
	v_mfma_f32_16x16x32_bf16 v[36:39], v[156:159], v[164:167], v[40:43]
	v_mfma_f32_16x16x32_bf16 v[68:71], v[160:163], v[168:171], v[36:39]
	v_mfma_f32_16x16x32_bf16 v[36:39], v[148:151], v[172:175], v[48:51]
	v_mfma_f32_16x16x32_bf16 v[52:55], v[152:155], v[176:179], v[36:39]
	v_mfma_f32_16x16x32_bf16 v[36:39], v[156:159], v[172:175], v[44:47]
	v_mfma_f32_16x16x32_bf16 v[24:27], v[148:151], v[196:199], v[24:27]
	v_mfma_f32_16x16x32_bf16 v[20:23], v[156:159], v[196:199], v[20:23]
	v_mfma_f32_16x16x32_bf16 v[8:11], v[148:151], v[204:207], v[8:11]
	v_mfma_f32_16x16x32_bf16 v[4:7], v[156:159], v[204:207], v[4:7]
	v_mfma_f32_16x16x32_bf16 v[44:47], v[160:163], v[176:179], v[36:39]
	v_mfma_f32_16x16x32_bf16 v[24:27], v[152:155], v[200:203], v[24:27]
	v_mfma_f32_16x16x32_bf16 v[20:23], v[160:163], v[200:203], v[20:23]
	v_mfma_f32_16x16x32_bf16 v[8:11], v[152:155], v[208:211], v[8:11]
	v_mfma_f32_16x16x32_bf16 v[4:7], v[160:163], v[208:211], v[4:7]
	s_setprio 0
	s_barrier
	s_add_u32 s12, s12, 0x100
	s_addc_u32 s13, s13, 0
	s_add_u32 s2, s2, 0x100
	s_addc_u32 s3, s3, 0
	s_cmp_ge_u32 s46, s73
	s_mov_b32 s14, s46
